# code warming issued by wave 2 at arrival, independent of wave 1's cache invalidate
# baseline (speedup 1.0000x reference)
; __device__ __forceinline__ void xcd_barrier(const XcdBarrier& b) {
;     asm volatile("s_waitcnt vmcnt(0)" ::: "memory");
;     __syncthreads();
;     if (threadIdx.x == 0) {
.Leinv_skip_0:
	v_readfirstlane_b32 s2, v152
	s_cmp_lg_u32 s2, 128
	s_cbranch_scc1 .Lwarm_skip_0
	s_getpc_b64 s[2:3]
